# v68 + mem rows bf16 conversion deferred from P0 to P1 head (odd XCDs)
# baseline (speedup 1.0000x reference)
.LBB0_40:
	s_add_u32 s34, s92, 0x8d00000
	s_addc_u32 s35, s93, 0
	s_cmp_eq_u32 s100, 0
	s_cbranch_scc1 .LBB0_50
	s_cmpk_gt_i32 s26, 0x7ff
	s_cbranch_scc1 .LBB0_50
	s_ashr_i32 s27, s26, 31
	v_readlane_b32 s36, v233, 2
	s_lshl_b64 s[0:1], s[26:27], 13
	v_readlane_b32 s38, v233, 4
	v_readlane_b32 s39, v233, 5
	s_add_u32 s0, s38, s0
	s_addc_u32 s1, s39, s1
	v_mov_b32_e32 v67, 0
	v_lshl_add_u64 v[2:3], s[0:1], 0, v[66:67]
	global_load_dwordx4 v[62:65], v66, s[0:1] nt
	global_load_dwordx4 v[58:61], v66, s[0:1] offset:1024 nt
	global_load_dwordx4 v[54:57], v66, s[0:1] offset:2048 nt
	global_load_dwordx4 v[46:49], v66, s[0:1] offset:3072 nt
	s_movk_i32 s0, 0x1000
	v_add_co_u32_e32 v2, vcc, s0, v2
	s_lshl_b64 s[0:1], s[26:27], 2
	s_nop 0
	v_addc_co_u32_e32 v3, vcc, 0, v3, vcc
	global_load_dwordx4 v[50:53], v[2:3], off nt
	global_load_dwordx4 v[42:45], v[2:3], off offset:1024 nt
	global_load_dwordx4 v[38:41], v[2:3], off offset:2048 nt
	global_load_dwordx4 v[34:37], v[2:3], off offset:3072 nt
	s_add_u32 s0, s92, s0
	s_addc_u32 s1, s93, s1
	s_add_u32 s8, s0, 0x10000
	v_mov_b32_e32 v69, v67
	s_addc_u32 s9, s1, 0
	s_ashr_i32 s97, s96, 31
	v_lshl_add_u64 v[70:71], s[38:39], 0, v[66:67]
	v_cmp_ne_u32_e64 s[4:5], 0, v76
	v_lshl_add_u64 v[68:69], s[34:35], 0, v[68:69]
	s_lshl_b64 s[10:11], s[96:97], 2
	v_mov_b32_e32 v66, 0x358637bd
	s_mov_b32 s14, 0xf800000
	v_mov_b32_e32 v74, 0x260
	v_readlane_b32 s37, v233, 3
	v_readlane_b32 s40, v233, 6
	v_readlane_b32 s41, v233, 7
	v_readlane_b32 s42, v233, 8
	v_readlane_b32 s43, v233, 9
	v_readlane_b32 s44, v233, 10
	v_readlane_b32 s45, v233, 11
	v_readlane_b32 s46, v233, 12
	v_readlane_b32 s47, v233, 13
	v_readlane_b32 s48, v233, 14
	v_readlane_b32 s49, v233, 15
	v_readlane_b32 s50, v233, 16
	v_readlane_b32 s51, v233, 17
	s_branch .LBB0_43

.LBB0_50:
	s_cmp_eq_u32 s100, 3
	s_cbranch_scc1 .Ldf_ret_mem
	v_lshl_add_u32 v2, s2, 9, v1
	s_movk_i32 s0, 0x4000
	s_lshl_b32 s4, s94, 9
	v_cmp_gt_i32_e32 vcc, s0, v2
	s_and_saveexec_b64 s[0:1], vcc
	s_cbranch_execz .LBB0_53
	v_ashrrev_i32_e32 v3, 31, v2
	v_lshl_add_u64 v[4:5], v[2:3], 2, s[92:93]
	s_mov_b64 s[8:9], 0x20000
	s_ashr_i32 s5, s4, 31
	v_lshl_add_u64 v[4:5], v[4:5], 0, s[8:9]
	s_lshl_b64 s[8:9], s[4:5], 2
	s_mov_b64 s[10:11], 0
	v_mov_b32_e32 v3, 0
	s_movk_i32 s5, 0x3fff
	v_mov_b32_e32 v6, v2

.Ldf_ret_p1:
	s_waitcnt lgkmcnt(0)
	v_mov_b32_e32 v1, v210
	v_and_b32_e32 v76, 63, v1
	v_lshlrev_b32_e32 v66, 4, v76
	v_lshlrev_b32_e32 v68, 3, v76
	v_readfirstlane_b32 s0, v1
	s_nop 3
	s_ashr_i32 s8, s0, 6
	v_readlane_b32 s2, v234, 2
	s_nop 3
	s_lshr_b32 s1, s2, 1
	s_lshl_b32 s1, s1, 3
	s_add_i32 s26, s8, s1
	s_movk_i32 s96, 0x400
	s_mov_b32 s100, 3
	s_branch .LBB0_40
